# combine phases 11 and 20: drop the top-of-loop wait for the previous row's stores (entry path keeps the full wait)
# baseline (speedup 1.0000x reference)
.LBB0_1890:
	s_or_b64 exec, exec, s[4:5]
	v_ashrrev_i32_e32 v0, 6, v13
	v_lshl_add_u32 v148, s2, 3, v0
	s_movk_i32 s3, 0x4000
	v_cmp_gt_i32_e32 vcc, s3, v148
	s_waitcnt lgkmcnt(0)
	s_barrier
	s_and_saveexec_b64 s[12:13], vcc
	s_cbranch_execz .LBB0_1895
	s_load_dwordx4 s[8:11], s[20:21], 0x1f8
	s_load_dwordx4 s[4:7], s[20:21], 0x1d0
	s_load_dwordx2 s[14:15], s[20:21], 0x190
	s_load_dwordx2 s[16:17], s[20:21], 0x180
	s_load_dwordx2 s[18:19], s[20:21], 0x158
	v_lshlrev_b32_e32 v0, 1, v148
	v_ashrrev_i32_e32 v1, 31, v0
	v_lshlrev_b64 v[0:1], 2, v[0:1]
	s_waitcnt lgkmcnt(0)
	v_lshl_add_u64 v[2:3], s[14:15], 0, v[0:1]
	global_load_dwordx2 v[2:3], v[2:3], off
	v_lshl_add_u64 v[0:1], s[16:17], 0, v[0:1]
	global_load_dwordx2 v[74:75], v[0:1], off
	v_and_b32_e32 v1, 64, v12
	v_add_u32_e32 v1, 64, v1
	v_xor_b32_e32 v4, 32, v12
	v_cmp_lt_i32_e32 vcc, v4, v1
	v_lshlrev_b32_e32 v0, 2, v12
	v_and_b32_e32 v0, 0xfc, v0
	v_cndmask_b32_e32 v4, v12, v4, vcc
	v_lshlrev_b32_e32 v149, 2, v4
	v_xor_b32_e32 v4, 16, v12
	v_cmp_lt_i32_e32 vcc, v4, v1
	s_load_dword s23, s[0:1], 0x230
	v_mov_b32_e32 v69, 0
	v_cndmask_b32_e32 v4, v12, v4, vcc
	v_lshlrev_b32_e32 v150, 2, v4
	v_xor_b32_e32 v4, 8, v12
	v_cmp_lt_i32_e32 vcc, v4, v1
	v_lshlrev_b32_e32 v68, 2, v0
	v_lshl_add_u64 v[70:71], s[8:9], 0, v[68:69]
	v_cndmask_b32_e32 v4, v12, v4, vcc
	v_lshlrev_b32_e32 v151, 2, v4
	v_xor_b32_e32 v4, 4, v12
	v_cmp_lt_i32_e32 vcc, v4, v1
	s_load_dwordx2 s[8:9], s[20:21], 0x30
	s_waitcnt lgkmcnt(0)
	s_lshl_b32 s22, s23, 3
	v_cndmask_b32_e32 v4, v12, v4, vcc
	v_lshlrev_b32_e32 v152, 2, v4
	v_xor_b32_e32 v4, 2, v12
	v_cmp_lt_i32_e32 vcc, v4, v1
	s_add_u32 s8, s8, 0x2000
	s_addc_u32 s9, s9, 0
	v_cndmask_b32_e32 v4, v12, v4, vcc
	v_lshlrev_b32_e32 v153, 2, v4
	v_xor_b32_e32 v4, 1, v12
	v_cmp_lt_i32_e32 vcc, v4, v1
	v_lshl_add_u64 v[72:73], s[10:11], 0, v[68:69]
	v_or_b32_e32 v6, 0x200, v0
	v_cndmask_b32_e32 v1, v12, v4, vcc
	v_or_b32_e32 v4, 0x100, v0
	v_lshl_add_u64 v[76:77], s[8:9], 0, v[68:69]
	v_lshlrev_b32_e32 v68, 2, v4
	v_or_b32_e32 v8, 0x300, v0
	v_lshl_add_u64 v[78:79], s[8:9], 0, v[68:69]
	v_lshlrev_b32_e32 v68, 2, v6
	v_or_b32_e32 v10, 0x400, v0
	v_lshl_add_u64 v[80:81], s[8:9], 0, v[68:69]
	v_lshlrev_b32_e32 v68, 2, v8
	v_or_b32_e32 v12, 0x500, v0
	v_lshl_add_u64 v[82:83], s[8:9], 0, v[68:69]
	v_lshlrev_b32_e32 v68, 2, v10
	v_or_b32_e32 v14, 0x600, v0
	v_lshl_add_u64 v[84:85], s[8:9], 0, v[68:69]
	v_lshlrev_b32_e32 v68, 2, v12
	v_or_b32_e32 v16, 0x700, v0
	v_lshl_add_u64 v[86:87], s[8:9], 0, v[68:69]
	v_lshlrev_b32_e32 v68, 2, v14
	v_lshl_add_u64 v[88:89], s[8:9], 0, v[68:69]
	v_lshlrev_b32_e32 v68, 2, v16
	v_lshl_add_u64 v[90:91], s[8:9], 0, v[68:69]
	v_lshlrev_b32_e32 v68, 1, v0
	v_lshl_add_u64 v[92:93], s[4:5], 0, v[68:69]
	v_lshl_add_u64 v[18:19], s[6:7], 0, v[68:69]
	s_mov_b64 s[4:5], 0xa000000
	v_lshlrev_b32_e32 v154, 2, v1
	v_lshl_add_u64 v[94:95], v[18:19], 0, s[4:5]
	v_add_lshl_u32 v96, v148, s22, 1
	s_lshl_b32 s23, s23, 4
	s_mov_b64 s[6:7], 0
	s_add_i32 s24, 0, 0x22000
	s_mov_b64 s[8:9], 0xa000
	v_lshlrev_b32_e32 v68, 2, v0
	v_lshlrev_b32_e32 v98, 2, v4
	v_lshlrev_b32_e32 v100, 2, v6
	v_lshlrev_b32_e32 v102, 2, v8
	v_lshlrev_b32_e32 v104, 2, v10
	s_movk_i32 s25, 0x1000
	v_lshlrev_b32_e32 v106, 2, v12
	v_lshlrev_b32_e32 v108, 2, v14
	v_lshlrev_b32_e32 v110, 2, v16
	s_movk_i32 s26, 0x3fff
	s_mov_b64 s[10:11], 0x3c000
	v_mov_b32_e32 v155, 0x358637bd
	s_mov_b32 s27, 0x800000
	s_mov_b64 s[20:21], 0x3e000
	s_waitcnt vmcnt(1)
	v_mov_b32_e32 v118, v3
	v_mov_b32_e32 v119, v2
	s_waitcnt vmcnt(0)
	s_branch .LBB0_1893

.LBB0_1893:
	v_bfe_u32 v2, v74, 16, 16
	v_lshl_add_u32 v2, v2, 2, s24
	v_bfe_u32 v3, v75, 16, 16
	v_ashrrev_i32_e32 v115, 31, v148
	ds_read_b32 v2, v2 offset:320
	v_lshl_add_u32 v3, v3, 2, s24
	v_lshrrev_b32_e32 v0, 20, v115
	ds_read_b32 v3, v3 offset:320
	v_add_u32_e32 v0, v148, v0
	v_ashrrev_i32_e32 v0, 12, v0
	v_mul_hi_i32_i24_e32 v1, 0xc000, v0
	v_mul_i32_i24_e32 v0, 0xc000, v0
	v_lshl_add_u64 v[116:117], s[18:19], 0, v[0:1]
	s_waitcnt lgkmcnt(1)
	v_add_u32_sdwa v0, v2, v74 dst_sel:DWORD dst_unused:UNUSED_PAD src0_sel:DWORD src1_sel:WORD_0
	v_mov_b32_e32 v1, v69
	v_mov_b32_e32 v114, v148
	v_lshlrev_b64 v[0:1], 12, v[0:1]
	s_waitcnt lgkmcnt(0)
	v_add_u32_sdwa v2, v3, v75 dst_sel:DWORD dst_unused:UNUSED_PAD src0_sel:DWORD src1_sel:WORD_0
	v_mov_b32_e32 v3, v69
	v_lshlrev_b64 v[4:5], 13, v[114:115]
	v_lshl_add_u64 v[28:29], v[116:117], 0, s[8:9]
	v_lshlrev_b64 v[2:3], 12, v[2:3]
	v_lshl_add_u64 v[4:5], v[70:71], 0, v[4:5]
	v_lshl_add_u64 v[30:31], v[94:95], 0, v[0:1]
	v_lshl_add_u64 v[0:1], v[28:29], 0, v[68:69]
	v_mov_b32_e32 v99, v69
	v_mov_b32_e32 v101, v69
	v_lshl_add_u64 v[34:35], v[94:95], 0, v[2:3]
	v_lshl_add_u64 v[2:3], v[28:29], 0, v[98:99]
	global_load_dwordx4 v[20:23], v[4:5], off
	global_load_dwordx4 v[8:11], v[4:5], off offset:1024
	global_load_dwordx4 v[24:27], v[0:1], off
	global_load_dwordx4 v[12:15], v[2:3], off
	v_lshl_add_u64 v[0:1], v[28:29], 0, v[100:101]
	v_mov_b32_e32 v103, v69
	v_mov_b32_e32 v105, v69
	global_load_dwordx2 v[144:145], v[30:31], off
	global_load_dwordx2 v[138:139], v[30:31], off offset:512
	global_load_dwordx2 v[130:131], v[30:31], off offset:1024
	global_load_dwordx2 v[122:123], v[30:31], off offset:1536
	global_load_dwordx2 v[146:147], v[34:35], off
	global_load_dwordx2 v[142:143], v[34:35], off offset:512
	global_load_dwordx2 v[134:135], v[34:35], off offset:1024
	global_load_dwordx2 v[126:127], v[34:35], off offset:1536
	v_lshl_add_u64 v[2:3], v[28:29], 0, v[102:103]
	global_load_dwordx4 v[56:59], v[4:5], off offset:2048
	global_load_dwordx4 v[16:19], v[4:5], off offset:3072
	global_load_dwordx4 v[64:67], v[0:1], off
	global_load_dwordx4 v[44:47], v[2:3], off
	v_lshl_add_u64 v[0:1], v[28:29], 0, v[104:105]
	v_add_co_u32_e32 v36, vcc, s25, v4
	v_mov_b32_e32 v107, v69
	v_mov_b32_e32 v109, v69
	v_addc_co_u32_e32 v37, vcc, 0, v5, vcc
	global_load_dwordx4 v[52:55], v[0:1], off
	v_lshl_add_u64 v[0:1], v[28:29], 0, v[106:107]
	v_lshl_add_u64 v[2:3], v[28:29], 0, v[108:109]
	global_load_dwordx4 v[60:63], v[36:37], off
	global_load_dwordx4 v[4:7], v[36:37], off offset:1024
	global_load_dwordx4 v[40:43], v[0:1], off
	s_nop 0
	global_load_dwordx4 v[0:3], v[2:3], off
	s_nop 0
	global_load_dwordx2 v[136:137], v[30:31], off offset:2048
	global_load_dwordx2 v[128:129], v[30:31], off offset:2560
	global_load_dwordx2 v[120:121], v[30:31], off offset:3072
	global_load_dwordx2 v[32:33], v[30:31], off offset:3584
	global_load_dwordx2 v[140:141], v[34:35], off offset:2048
	global_load_dwordx2 v[132:133], v[34:35], off offset:2560
	global_load_dwordx2 v[124:125], v[34:35], off offset:3072
	s_nop 0
	global_load_dwordx2 v[34:35], v[34:35], off offset:3584
	v_mov_b32_e32 v111, v69
	v_lshl_add_u64 v[38:39], v[28:29], 0, v[110:111]
	global_load_dwordx4 v[48:51], v[36:37], off offset:2048
	global_load_dwordx4 v[28:31], v[36:37], off offset:3072
	s_nop 0
	global_load_dwordx4 v[36:39], v[38:39], off
	v_add_u32_e32 v148, s22, v148
	v_cmp_lt_i32_e64 s[4:5], s26, v148
	v_cmp_gt_i32_e32 vcc, s3, v148
	s_or_b64 s[6:7], s[4:5], s[6:7]
	v_mov_b32_e32 v113, v118
	v_mov_b32_e32 v112, v119
	s_and_saveexec_b64 s[4:5], vcc
	s_cbranch_execz .LBB0_1892
	v_ashrrev_i32_e32 v97, 31, v96
	v_lshlrev_b64 v[74:75], 2, v[96:97]
	v_lshl_add_u64 v[112:113], s[14:15], 0, v[74:75]
	v_lshl_add_u64 v[74:75], s[16:17], 0, v[74:75]
	global_load_dwordx2 v[112:113], v[112:113], off
	s_nop 0
	global_load_dwordx2 v[74:75], v[74:75], off
	s_branch .LBB0_1892

.LBB0_2543:
	s_or_b64 exec, exec, s[6:7]
	v_ashrrev_i32_e32 v0, 6, v13
	v_lshl_add_u32 v130, s2, 3, v0
	s_movk_i32 s16, 0x4000
	v_cmp_gt_i32_e32 vcc, s16, v130
	s_waitcnt lgkmcnt(0)
	s_barrier
	s_and_saveexec_b64 s[6:7], vcc
	s_cbranch_execz .LBB0_2548
	s_load_dwordx2 s[8:9], s[4:5], 0x190
	s_load_dwordx2 s[10:11], s[4:5], 0x180
	v_lshlrev_b32_e32 v0, 1, v130
	v_ashrrev_i32_e32 v1, 31, v0
	v_lshlrev_b64 v[0:1], 2, v[0:1]
	s_waitcnt lgkmcnt(0)
	v_lshl_add_u64 v[2:3], s[8:9], 0, v[0:1]
	global_load_dwordx2 v[2:3], v[2:3], off
	v_lshl_add_u64 v[0:1], s[10:11], 0, v[0:1]
	global_load_dwordx2 v[66:67], v[0:1], off
	s_load_dwordx2 s[2:3], s[4:5], 0x148
	s_load_dwordx2 s[12:13], s[4:5], 0x158
	s_load_dwordx2 s[20:21], s[4:5], 0x1f8
	s_load_dwordx2 s[22:23], s[4:5], 0x1d8
	s_load_dword s26, s[0:1], 0x230
	v_lshlrev_b32_e32 v0, 2, v12
	v_and_b32_e32 v0, 0xfc, v0
	v_mov_b32_e32 v65, 0
	v_lshlrev_b32_e32 v64, 2, v0
	s_waitcnt lgkmcnt(0)
	v_lshl_add_u64 v[84:85], s[20:21], 0, v[64:65]
	v_lshl_add_u64 v[86:87], s[2:3], 0, v[64:65]
	v_lshlrev_b32_e32 v64, 1, v0
	s_mov_b64 s[24:25], 0xa000000
	v_or_b32_e32 v4, 0x100, v0
	v_or_b32_e32 v6, 0x200, v0
	v_or_b32_e32 v8, 0x300, v0
	v_or_b32_e32 v10, 0x400, v0
	v_or_b32_e32 v12, 0x500, v0
	v_or_b32_e32 v14, 0x600, v0
	v_or_b32_e32 v16, 0x700, v0
	v_lshlrev_b32_e32 v68, 2, v0
	s_lshl_b32 s20, s26, 3
	v_lshl_add_u64 v[0:1], s[22:23], 0, v[64:65]
	s_mov_b64 s[4:5], 0
	s_add_i32 s17, 0, 0x22000
	s_mov_b64 s[14:15], 0xa000
	s_movk_i32 s18, 0x1000
	s_movk_i32 s19, 0x3fff
	v_mov_b32_e32 v69, v65
	v_mov_b32_e32 v71, v65
	v_mov_b32_e32 v73, v65
	v_mov_b32_e32 v75, v65
	v_mov_b32_e32 v77, v65
	v_mov_b32_e32 v79, v65
	v_mov_b32_e32 v81, v65
	v_mov_b32_e32 v83, v65
	v_lshlrev_b32_e32 v70, 2, v4
	v_lshlrev_b32_e32 v72, 2, v6
	v_lshlrev_b32_e32 v74, 2, v8
	v_lshlrev_b32_e32 v76, 2, v10
	v_lshlrev_b32_e32 v78, 2, v12
	v_lshlrev_b32_e32 v80, 2, v14
	v_lshlrev_b32_e32 v82, 2, v16
	s_lshl_b32 s21, s26, 4
	v_add_lshl_u32 v88, v130, s20, 1
	v_lshl_add_u64 v[90:91], v[0:1], 0, s[24:25]
	s_waitcnt vmcnt(1)
	v_mov_b32_e32 v92, v3
	v_mov_b32_e32 v93, v2
	s_waitcnt vmcnt(0)
	s_branch .LBB0_2546

.LBB0_2546:
	v_ashrrev_i32_e32 v125, 31, v130
	v_bfe_u32 v2, v66, 16, 16
	v_lshrrev_b32_e32 v0, 20, v125
	v_lshl_add_u32 v2, v2, 2, s17
	v_bfe_u32 v3, v67, 16, 16
	v_add_u32_e32 v0, v130, v0
	ds_read_b32 v2, v2 offset:320
	v_lshl_add_u32 v3, v3, 2, s17
	v_ashrrev_i32_e32 v0, 12, v0
	ds_read_b32 v4, v3 offset:320
	v_add_u32_e32 v0, 5, v0
	v_mul_hi_i32_i24_e32 v1, 0xc000, v0
	v_mul_i32_i24_e32 v0, 0xc000, v0
	v_lshl_add_u64 v[0:1], s[12:13], 0, v[0:1]
	v_mov_b32_e32 v124, v130
	s_waitcnt lgkmcnt(1)
	v_add_u32_sdwa v64, v2, v66 dst_sel:DWORD dst_unused:UNUSED_PAD src0_sel:DWORD src1_sel:WORD_0
	v_lshlrev_b64 v[6:7], 13, v[124:125]
	v_lshl_add_u64 v[8:9], v[0:1], 0, s[14:15]
	v_lshlrev_b64 v[2:3], 12, v[64:65]
	s_waitcnt lgkmcnt(0)
	v_add_u32_sdwa v64, v4, v67 dst_sel:DWORD dst_unused:UNUSED_PAD src0_sel:DWORD src1_sel:WORD_0
	v_lshl_add_u64 v[6:7], v[84:85], 0, v[6:7]
	v_lshl_add_u64 v[0:1], v[8:9], 0, v[68:69]
	v_lshlrev_b64 v[4:5], 12, v[64:65]
	v_lshl_add_u64 v[10:11], v[90:91], 0, v[2:3]
	v_lshl_add_u64 v[2:3], v[8:9], 0, v[70:71]
	global_load_dwordx4 v[52:55], v[6:7], off
	global_load_dwordx4 v[24:27], v[6:7], off offset:1024
	global_load_dwordx4 v[60:63], v[0:1], off
	global_load_dwordx4 v[40:43], v[2:3], off
	v_lshl_add_u64 v[0:1], v[8:9], 0, v[72:73]
	v_add_co_u32_e32 v14, vcc, s18, v6
	v_lshl_add_u64 v[12:13], v[90:91], 0, v[4:5]
	global_load_dwordx2 v[126:127], v[10:11], off
	global_load_dwordx2 v[120:121], v[10:11], off offset:512
	global_load_dwordx2 v[112:113], v[10:11], off offset:1024
	global_load_dwordx2 v[104:105], v[10:11], off offset:1536
	global_load_dwordx2 v[128:129], v[12:13], off
	global_load_dwordx2 v[122:123], v[12:13], off offset:512
	global_load_dwordx2 v[116:117], v[12:13], off offset:1024
	global_load_dwordx2 v[108:109], v[12:13], off offset:1536
	v_lshl_add_u64 v[2:3], v[8:9], 0, v[74:75]
	global_load_dwordx4 v[48:51], v[6:7], off offset:2048
	global_load_dwordx4 v[20:23], v[6:7], off offset:3072
	global_load_dwordx4 v[56:59], v[0:1], off
	global_load_dwordx4 v[28:31], v[2:3], off
	v_lshl_add_u64 v[0:1], v[8:9], 0, v[76:77]
	v_addc_co_u32_e32 v15, vcc, 0, v7, vcc
	v_lshl_add_u64 v[36:37], v[8:9], 0, v[78:79]
	global_load_dwordx4 v[32:35], v[0:1], off
	global_load_dwordx4 v[44:47], v[14:15], off
	global_load_dwordx4 v[4:7], v[14:15], off offset:1024
	v_lshl_add_u64 v[38:39], v[8:9], 0, v[80:81]
	global_load_dwordx4 v[16:19], v[36:37], off
	global_load_dwordx4 v[0:3], v[38:39], off
	global_load_dwordx2 v[114:115], v[10:11], off offset:2048
	global_load_dwordx2 v[106:107], v[10:11], off offset:2560
	global_load_dwordx2 v[100:101], v[10:11], off offset:3072
	global_load_dwordx2 v[96:97], v[10:11], off offset:3584
	global_load_dwordx2 v[118:119], v[12:13], off offset:2048
	global_load_dwordx2 v[110:111], v[12:13], off offset:2560
	global_load_dwordx2 v[102:103], v[12:13], off offset:3072
	global_load_dwordx2 v[98:99], v[12:13], off offset:3584
	v_lshl_add_u64 v[12:13], v[8:9], 0, v[82:83]
	global_load_dwordx4 v[36:39], v[14:15], off offset:2048
	global_load_dwordx4 v[8:11], v[14:15], off offset:3072
	s_nop 0
	global_load_dwordx4 v[12:15], v[12:13], off
	v_add_u32_e32 v130, s20, v130
	v_cmp_lt_i32_e64 s[2:3], s19, v130
	v_cmp_gt_i32_e32 vcc, s16, v130
	s_or_b64 s[4:5], s[2:3], s[4:5]
	v_mov_b32_e32 v95, v92
	v_mov_b32_e32 v94, v93
	s_and_saveexec_b64 s[2:3], vcc
	s_cbranch_execz .LBB0_2545
	v_ashrrev_i32_e32 v89, 31, v88
	v_lshlrev_b64 v[66:67], 2, v[88:89]
	v_lshl_add_u64 v[94:95], s[8:9], 0, v[66:67]
	v_lshl_add_u64 v[66:67], s[10:11], 0, v[66:67]
	global_load_dwordx2 v[94:95], v[94:95], off
	s_nop 0
	global_load_dwordx2 v[66:67], v[66:67], off
	s_branch .LBB0_2545
